# previous + Up-GEMM epilogue: per-row rstd computed once per workgroup into an LDS table (removes the per-wave 16-partial reductions, 137 instructions per tile per wave)
# speedup vs baseline: 1.0114x; 1.0000x over previous
; __device__ __forceinline__ int lane_id_v() { int l; asm volatile("v_mbcnt_lo_u32_b32 %0, -1, 0\n\tv_mbcnt_hi_u32_b32 %0, -1, %0" : "=v"(l)); return l; }
; #define LAS __attribute__((address_space(3)))
; __device__ __forceinline__ void rows_rstd8_lds(const LAS unsigned char* xl, int lrow0, int fq, float (&rs)[8]) {
; #pragma unroll
;     for (int i = 0; i < 8; ++i) { const f32x4 p = *(const LAS f32x4*)(xl + (lrow0 + (i >> 2) * 128 + (i & 3) * 16) * 64 + 16 * fq);
;         float t = (p[0] + p[1]) + (p[2] + p[3]); t += __shfl_xor(t, 16); t += __shfl_xor(t, 32); rs[i] = rsqrtf(t * (1.0f / D) + EPS); }
; }
;     __device__ __forceinline__ void operator()(const f32x4 (&acc)[2][2][4][2], const pg8::Unit& u, int wr, int wc, int fr_, int fq_) const {
;         const int lane_ = pg8::lane_id_v(); const int fr = lane_ & 15, fq = lane_ >> 4;
;         const int lrow0 = u.pm * 256 + wr * 64 + fr;
;         const int b = batch_of(rowbase + u.pm * 256);
;         f32x4 sv[2][2];
; #pragma unroll
;         for (int bj = 0; bj < 2; ++bj)
; #pragma unroll
;             for (int n = 0; n < 2; ++n) sv[bj][n] = *(const LAS f32x4*)(xl + 16384 + (bj * 128 + wc * 32 + 8 * fq + 4 * n) * 4);
;         float rs8[8]; rows_rstd8_lds(xl, wr * 64 + fr, fq, rs8);
;         const int hcol = u.pn * 128 + wc * 32 + 8 * fq;
; #pragma unroll
;         for (int ai = 0; ai < 2; ++ai)
; #pragma unroll
;             for (int m = 0; m < 4; ++m) {
;                 const int lr = lrow0 + ai * 128 + m * 16;
;                 const float rs = rs8[ai * 4 + m];
;                 const f32x4 g0 = acc[ai][0][m][0] * rs + sv[0][0], g1 = acc[ai][0][m][1] * rs + sv[0][1];
;                 const f32x4 u0 = acc[ai][1][m][0] * rs + sv[1][0], u1 = acc[ai][1][m][1] * rs + sv[1][1];
.LBB0_379:
	v_mbcnt_lo_u32_b32 v228, -1, 0
	v_mbcnt_hi_u32_b32 v228, -1, v228
	s_lshl_b32 s26, s91, 1
	s_add_i32 s26, s26, s15
	v_lshrrev_b32_e32 v224, 1, v228
	v_add_u32_e32 v224, s26, v224
	v_and_b32_e32 v225, 1, v228
	v_lshlrev_b32_e32 v227, 2, v224
	v_lshlrev_b32_e32 v224, 6, v224
	v_lshl_add_u32 v224, v225, 5, v224
	v_add_u32_e32 v224, 0x22400, v224
	v_add_u32_e32 v227, 0x26800, v227
	ds_read_b128 v[216:219], v224
	ds_read_b128 v[220:223], v224 offset:16
	v_mov_b32_e32 v226, 0x358637bd
	s_waitcnt lgkmcnt(0)
	v_add_f32_e32 v216, v216, v217
	v_add_f32_e32 v218, v218, v219
	v_add_f32_e32 v220, v220, v221
	v_add_f32_e32 v222, v222, v223
	v_add_f32_e32 v216, v216, v218
	v_add_f32_e32 v220, v220, v222
	v_add_f32_e32 v216, v216, v220
	s_nop 1
	v_add_f32_dpp v225, v216, v216 quad_perm:[1,0,3,2] row_mask:0xf bank_mask:0xf
	v_fma_f32 v225, v225, s16, v226
	v_rsq_f32_e32 v225, v225
	s_nop 0
	ds_write_b32 v227, v225
	v_and_b32_e32 v224, 15, v228
	v_add_u32_e32 v224, s91, v224
	v_lshlrev_b32_e32 v224, 2, v224
	v_add_u32_e32 v224, 0x26800, v224
	s_waitcnt lgkmcnt(0)
	s_barrier
	ds_read_b32 v208, v224
	ds_read_b32 v209, v224 offset:64
	ds_read_b32 v210, v224 offset:128
	ds_read_b32 v211, v224 offset:192
	ds_read_b32 v212, v224 offset:512
	ds_read_b32 v213, v224 offset:576
	ds_read_b32 v214, v224 offset:640
	ds_read_b32 v215, v224 offset:704
	s_waitcnt lgkmcnt(0)
	v_mbcnt_lo_u32_b32 v158, -1, 0
	v_mbcnt_hi_u32_b32 v158, -1, v158
	s_add_i32 s23, s23, s91
	v_and_b32_e32 v159, 15, v158
	v_or_b32_e32 v165, s23, v159
	v_ashrrev_i32_e32 v167, 4, v158
	v_readlane_b32 s26, v252, 22
	s_add_i32 s23, 0, 0x22400
	v_lshl_add_u32 v80, v167, 5, s26
	ds_read_b128 v[92:95], v80
	ds_read_b128 v[88:91], v80 offset:16
	ds_read_b128 v[84:87], v80 offset:512
	ds_read_b128 v[80:83], v80 offset:528
	s_mov_b32 s26, 0x358637bd
	s_lshl_b32 s2, s2, 7
	s_waitcnt lgkmcnt(0)
	s_waitcnt lgkmcnt(0)
	s_or_b32 s2, s2, s15
	s_mov_b64 s[76:77], s[62:63]
	s_waitcnt lgkmcnt(0)
	s_waitcnt lgkmcnt(0)
	s_nop 0
	s_nop 0
	s_nop 0
	v_mov_b32_e32 v172, v208
	s_waitcnt lgkmcnt(0)
	v_mov_b32_e32 v170, v209
	v_pk_fma_f32 v[126:127], v[126:127], v[170:171], v[94:95] op_sel_hi:[1,0,1]
	v_pk_fma_f32 v[124:125], v[124:125], v[170:171], v[92:93] op_sel_hi:[1,0,1]
	s_waitcnt lgkmcnt(0)
	v_pk_fma_f32 v[116:117], v[116:117], v[170:171], v[84:85] op_sel_hi:[1,0,1]
	v_pk_fma_f32 v[118:119], v[118:119], v[170:171], v[86:87] op_sel_hi:[1,0,1]
	v_pk_mul_f32 v[116:117], v[124:125], v[116:117]
	v_pk_fma_f32 v[120:121], v[120:121], v[170:171], v[88:89] op_sel_hi:[1,0,1]
	s_waitcnt lgkmcnt(0)
	v_pk_mul_f32 v[118:119], v[126:127], v[118:119]
	v_pk_fma_f32 v[112:113], v[112:113], v[170:171], v[80:81] op_sel_hi:[1,0,1]
	v_pk_fma_f32 v[122:123], v[122:123], v[170:171], v[90:91] op_sel_hi:[1,0,1]
	v_pk_mul_f32 v[112:113], v[120:121], v[112:113]
	s_waitcnt lgkmcnt(0)
	v_pk_fma_f32 v[114:115], v[114:115], v[170:171], v[82:83] op_sel_hi:[1,0,1]
	v_pk_mul_f32 v[114:115], v[122:123], v[114:115]
	s_nop 0
	s_nop 0
	v_mov_b32_e32 v168, v210
	v_pk_fma_f32 v[110:111], v[110:111], v[168:169], v[94:95] op_sel_hi:[1,0,1]
	v_pk_fma_f32 v[108:109], v[108:109], v[168:169], v[92:93] op_sel_hi:[1,0,1]
	v_pk_fma_f32 v[100:101], v[100:101], v[168:169], v[84:85] op_sel_hi:[1,0,1]
	s_waitcnt lgkmcnt(0)
	v_mov_b32_e32 v166, v211
	v_pk_mul_f32 v[100:101], v[108:109], v[100:101]
	v_pk_fma_f32 v[102:103], v[102:103], v[168:169], v[86:87] op_sel_hi:[1,0,1]
	s_waitcnt lgkmcnt(0)
	v_pk_fma_f32 v[104:105], v[104:105], v[168:169], v[88:89] op_sel_hi:[1,0,1]
	v_pk_mul_f32 v[102:103], v[110:111], v[102:103]
	v_pk_fma_f32 v[96:97], v[96:97], v[168:169], v[80:81] op_sel_hi:[1,0,1]
	v_pk_fma_f32 v[106:107], v[106:107], v[168:169], v[90:91] op_sel_hi:[1,0,1]
	s_waitcnt lgkmcnt(0)
	v_pk_mul_f32 v[96:97], v[104:105], v[96:97]
	v_pk_fma_f32 v[98:99], v[98:99], v[168:169], v[82:83] op_sel_hi:[1,0,1]
	v_pk_fma_f32 v[78:79], v[78:79], v[166:167], v[94:95] op_sel_hi:[1,0,1]
	v_pk_mul_f32 v[98:99], v[106:107], v[98:99]
	s_waitcnt lgkmcnt(0)
	v_pk_fma_f32 v[76:77], v[76:77], v[166:167], v[92:93] op_sel_hi:[1,0,1]
	v_pk_fma_f32 v[68:69], v[68:69], v[166:167], v[84:85] op_sel_hi:[1,0,1]
	v_pk_mul_f32 v[68:69], v[76:77], v[68:69]
	v_pk_fma_f32 v[70:71], v[70:71], v[166:167], v[86:87] op_sel_hi:[1,0,1]
	v_pk_fma_f32 v[72:73], v[72:73], v[166:167], v[88:89] op_sel_hi:[1,0,1]
	v_pk_mul_f32 v[70:71], v[78:79], v[70:71]
	v_mov_b32_e32 v164, v212
	v_pk_fma_f32 v[64:65], v[64:65], v[166:167], v[80:81] op_sel_hi:[1,0,1]
	v_pk_fma_f32 v[74:75], v[74:75], v[166:167], v[90:91] op_sel_hi:[1,0,1]
	v_pk_mul_f32 v[64:65], v[72:73], v[64:65]
	s_waitcnt lgkmcnt(0)
	v_pk_fma_f32 v[142:143], v[142:143], v[172:173], v[94:95] op_sel_hi:[1,0,1]
	v_pk_fma_f32 v[140:141], v[140:141], v[172:173], v[92:93] op_sel_hi:[1,0,1]
	v_pk_fma_f32 v[132:133], v[132:133], v[172:173], v[84:85] op_sel_hi:[1,0,1]
	v_mov_b32_e32 v162, v213
	v_pk_fma_f32 v[138:139], v[138:139], v[172:173], v[90:91] op_sel_hi:[1,0,1]
	v_pk_fma_f32 v[136:137], v[136:137], v[172:173], v[88:89] op_sel_hi:[1,0,1]
	v_pk_fma_f32 v[134:135], v[134:135], v[172:173], v[86:87] op_sel_hi:[1,0,1]
	v_pk_fma_f32 v[128:129], v[128:129], v[172:173], v[80:81] op_sel_hi:[1,0,1]
	v_pk_fma_f32 v[130:131], v[130:131], v[172:173], v[82:83] op_sel_hi:[1,0,1]
	v_pk_mul_f32 v[172:173], v[140:141], s[88:89] op_sel_hi:[1,0]
	v_pk_mul_f32 v[132:133], v[140:141], v[132:133]
	v_pk_mul_f32 v[140:141], v[142:143], s[88:89] op_sel_hi:[1,0]
	s_waitcnt lgkmcnt(0)
; __device__ __forceinline__ unsigned cvt_pk_bf16(float lo, float hi) { unsigned r; asm volatile("v_cvt_pk_bf16_f32 %0, %1, %2" : "=v"(r) : "v"(lo), "v"(hi)); return r; }
; __device__ __forceinline__ f32x2 silu_mul_pk(f32x2 g, f32x2 u) {
;     const f32x2 t = g * (-1.4426950409f);
;     f32x2 e; e.x = __builtin_amdgcn_exp2f(t.x); e.y = __builtin_amdgcn_exp2f(t.y);
;     const f32x2 d = e + 1.0f;
;     f32x2 r; r.x = __builtin_amdgcn_rcpf(d.x); r.y = __builtin_amdgcn_rcpf(d.y);
;     return (g * u) * r;
; }
;     __device__ __forceinline__ void operator()(const f32x4 (&acc)[2][2][4][2], const pg8::Unit& u, int wr, int wc, int fr_, int fq_) const {
;     ...
;             for (int m = 0; m < 4; ++m) {
;                 const int lr = lrow0 + ai * 128 + m * 16;
;                 const float rs = rs8[ai * 4 + m];
;                 const f32x4 g0 = acc[ai][0][m][0] * rs + sv[0][0], g1 = acc[ai][0][m][1] * rs + sv[0][1];
;                 const f32x4 u0 = acc[ai][1][m][0] * rs + sv[1][0], u1 = acc[ai][1][m][1] * rs + sv[1][1];
;                 const f32x2 ha = pg8::silu_mul_pk((f32x2){g0[0], g0[1]}, (f32x2){u0[0], u0[1]}), hb = pg8::silu_mul_pk((f32x2){g0[2], g0[3]}, (f32x2){u0[2], u0[3]});
;                 const f32x2 hc = pg8::silu_mul_pk((f32x2){g1[0], g1[1]}, (f32x2){u1[0], u1[1]}), hd = pg8::silu_mul_pk((f32x2){g1[2], g1[3]}, (f32x2){u1[2], u1[3]});
;                 u32x4 w; w.x = cvt_pk_bf16(ha.x, ha.y); w.y = cvt_pk_bf16(hb.x, hb.y); w.z = cvt_pk_bf16(hc.x, hc.y); w.w = cvt_pk_bf16(hd.x, hd.y);
;                 *(u32x4*)(H + (size_t)lr * FF + hcol) = w;
	v_exp_f32_e32 v140, v140
	v_exp_f32_e32 v141, v141
	s_nop 0
	v_pk_add_f32 v[140:141], v[140:141], 1.0 op_sel_hi:[1,0]
	v_rcp_f32_e32 v140, v140
	v_rcp_f32_e32 v141, v141
	v_pk_mul_f32 v[134:135], v[142:143], v[134:135]
	v_exp_f32_e32 v172, v172
	v_pk_mul_f32 v[134:135], v[134:135], v[140:141]
	v_pk_mul_f32 v[140:141], v[136:137], s[88:89] op_sel_hi:[1,0]
	v_exp_f32_e32 v173, v173
	v_exp_f32_e32 v140, v140
	v_exp_f32_e32 v141, v141
	v_pk_mul_f32 v[128:129], v[136:137], v[128:129]
	v_pk_mul_f32 v[136:137], v[138:139], s[88:89] op_sel_hi:[1,0]
	s_waitcnt lgkmcnt(0)
	v_exp_f32_e32 v136, v136
	v_exp_f32_e32 v137, v137
	v_pk_add_f32 v[172:173], v[172:173], 1.0 op_sel_hi:[1,0]
	v_pk_add_f32 v[140:141], v[140:141], 1.0 op_sel_hi:[1,0]
	v_rcp_f32_e32 v172, v172
	v_rcp_f32_e32 v173, v173
	v_rcp_f32_e32 v140, v140
	v_rcp_f32_e32 v141, v141
	v_pk_add_f32 v[136:137], v[136:137], 1.0 op_sel_hi:[1,0]
	s_waitcnt lgkmcnt(0)
	v_rcp_f32_e32 v136, v136
	v_rcp_f32_e32 v137, v137
	v_lshl_add_u32 v174, v167, 3, s2
	v_pk_mul_f32 v[132:133], v[132:133], v[172:173]
	v_pk_mul_f32 v[130:131], v[138:139], v[130:131]
	v_pk_mul_f32 v[128:129], v[128:129], v[140:141]
	v_ashrrev_i32_e32 v175, 31, v174
	v_pk_mul_f32 v[130:131], v[130:131], v[136:137]
	v_cvt_pk_bf16_f32 v132, v132, v133
	v_cvt_pk_bf16_f32 v133, v134, v135
	v_cvt_pk_bf16_f32 v134, v128, v129
	v_mov_b64_e32 v[128:129], s[30:31]
	s_movk_i32 s2, 0x1600
	v_cvt_pk_bf16_f32 v135, v130, v131
	v_mad_i64_i32 v[136:137], s[26:27], v165, s2, v[128:129]
	v_lshlrev_b64 v[130:131], 1, v[174:175]
	v_lshl_add_u64 v[136:137], v[136:137], 0, v[130:131]
	global_store_dwordx4 v[136:137], v[132:135], off
	v_pk_fma_f32 v[66:67], v[66:67], v[166:167], v[82:83] op_sel_hi:[1,0,1]
	v_pk_fma_f32 v[62:63], v[62:63], v[164:165], v[94:95] op_sel_hi:[1,0,1]
	v_pk_mul_f32 v[132:133], v[124:125], s[88:89] op_sel_hi:[1,0]
	v_pk_mul_f32 v[124:125], v[126:127], s[88:89] op_sel_hi:[1,0]
	v_exp_f32_e32 v132, v132
	v_exp_f32_e32 v124, v124
	v_exp_f32_e32 v125, v125
	v_exp_f32_e32 v133, v133
	v_or_b32_e32 v134, 16, v165
	v_pk_mul_f32 v[66:67], v[74:75], v[66:67]
	v_pk_add_f32 v[124:125], v[124:125], 1.0 op_sel_hi:[1,0]
	v_pk_add_f32 v[132:133], v[132:133], 1.0 op_sel_hi:[1,0]
	v_rcp_f32_e32 v124, v124
	v_rcp_f32_e32 v125, v125
	v_rcp_f32_e32 v132, v132
	v_rcp_f32_e32 v133, v133
	v_pk_fma_f32 v[60:61], v[60:61], v[164:165], v[92:93] op_sel_hi:[1,0,1]
	v_pk_mul_f32 v[118:119], v[118:119], v[124:125]
	v_pk_mul_f32 v[124:125], v[120:121], s[88:89] op_sel_hi:[1,0]
	v_pk_mul_f32 v[116:117], v[116:117], v[132:133]
	v_exp_f32_e32 v124, v124
	v_exp_f32_e32 v125, v125
	v_pk_fma_f32 v[52:53], v[52:53], v[164:165], v[84:85] op_sel_hi:[1,0,1]
	v_pk_fma_f32 v[54:55], v[54:55], v[164:165], v[86:87] op_sel_hi:[1,0,1]
	v_pk_mul_f32 v[52:53], v[60:61], v[52:53]
	v_pk_add_f32 v[124:125], v[124:125], 1.0 op_sel_hi:[1,0]
	v_pk_fma_f32 v[56:57], v[56:57], v[164:165], v[88:89] op_sel_hi:[1,0,1]
	v_rcp_f32_e32 v124, v124
	v_rcp_f32_e32 v125, v125
	v_pk_mul_f32 v[54:55], v[62:63], v[54:55]
	v_pk_fma_f32 v[48:49], v[48:49], v[164:165], v[80:81] op_sel_hi:[1,0,1]
	v_pk_fma_f32 v[58:59], v[58:59], v[164:165], v[90:91] op_sel_hi:[1,0,1]
	v_pk_mul_f32 v[120:121], v[112:113], v[124:125]
	v_pk_mul_f32 v[112:113], v[122:123], s[88:89] op_sel_hi:[1,0]
	v_pk_mul_f32 v[48:49], v[56:57], v[48:49]
	v_exp_f32_e32 v112, v112
	v_exp_f32_e32 v113, v113
	v_pk_fma_f32 v[50:51], v[50:51], v[164:165], v[82:83] op_sel_hi:[1,0,1]
	v_pk_fma_f32 v[46:47], v[46:47], v[162:163], v[94:95] op_sel_hi:[1,0,1]
	v_pk_mul_f32 v[50:51], v[58:59], v[50:51]
	v_pk_add_f32 v[112:113], v[112:113], 1.0 op_sel_hi:[1,0]
	v_pk_fma_f32 v[44:45], v[44:45], v[162:163], v[92:93] op_sel_hi:[1,0,1]
	v_rcp_f32_e32 v112, v112
	v_rcp_f32_e32 v113, v113
	v_pk_fma_f32 v[36:37], v[36:37], v[162:163], v[84:85] op_sel_hi:[1,0,1]
	v_pk_fma_f32 v[38:39], v[38:39], v[162:163], v[86:87] op_sel_hi:[1,0,1]
	v_pk_mul_f32 v[36:37], v[44:45], v[36:37]
	v_pk_mul_f32 v[122:123], v[114:115], v[112:113]
	v_cvt_pk_bf16_f32 v112, v116, v117
	v_mad_i64_i32 v[116:117], s[26:27], v134, s2, v[128:129]
	v_cvt_pk_bf16_f32 v113, v118, v119
	v_lshl_add_u64 v[116:117], v[116:117], 0, v[130:131]
	v_cvt_pk_bf16_f32 v114, v120, v121
	v_cvt_pk_bf16_f32 v115, v122, v123
	global_store_dwordx4 v[116:117], v[112:115], off
	v_pk_fma_f32 v[40:41], v[40:41], v[162:163], v[88:89] op_sel_hi:[1,0,1]
	v_pk_mul_f32 v[38:39], v[46:47], v[38:39]
	v_pk_mul_f32 v[112:113], v[108:109], s[88:89] op_sel_hi:[1,0]
	v_pk_mul_f32 v[108:109], v[110:111], s[88:89] op_sel_hi:[1,0]
	v_exp_f32_e32 v112, v112
	v_exp_f32_e32 v108, v108
	v_exp_f32_e32 v109, v109
	v_exp_f32_e32 v113, v113
	v_or_b32_e32 v114, 32, v165
	v_pk_fma_f32 v[32:33], v[32:33], v[162:163], v[80:81] op_sel_hi:[1,0,1]
	v_pk_add_f32 v[108:109], v[108:109], 1.0 op_sel_hi:[1,0]
	v_pk_add_f32 v[112:113], v[112:113], 1.0 op_sel_hi:[1,0]
	v_rcp_f32_e32 v108, v108
	v_rcp_f32_e32 v109, v109
	v_rcp_f32_e32 v112, v112
	v_rcp_f32_e32 v113, v113
	v_pk_fma_f32 v[42:43], v[42:43], v[162:163], v[90:91] op_sel_hi:[1,0,1]
	v_pk_mul_f32 v[102:103], v[102:103], v[108:109]
	v_pk_mul_f32 v[108:109], v[104:105], s[88:89] op_sel_hi:[1,0]
	v_pk_mul_f32 v[100:101], v[100:101], v[112:113]
	v_exp_f32_e32 v108, v108
	v_exp_f32_e32 v109, v109
	v_pk_mul_f32 v[32:33], v[40:41], v[32:33]
	v_pk_add_f32 v[108:109], v[108:109], 1.0 op_sel_hi:[1,0]
	v_pk_fma_f32 v[34:35], v[34:35], v[162:163], v[82:83] op_sel_hi:[1,0,1]
	v_rcp_f32_e32 v108, v108
	v_rcp_f32_e32 v109, v109
	v_pk_mul_f32 v[34:35], v[42:43], v[34:35]
	v_pk_mul_f32 v[104:105], v[96:97], v[108:109]
	v_pk_mul_f32 v[96:97], v[106:107], s[88:89] op_sel_hi:[1,0]
	v_exp_f32_e32 v96, v96
; __device__ __forceinline__ unsigned cvt_pk_bf16(float lo, float hi) { unsigned r; asm volatile("v_cvt_pk_bf16_f32 %0, %1, %2" : "=v"(r) : "v"(lo), "v"(hi)); return r; }
; __device__ __forceinline__ f32x2 silu_mul_pk(f32x2 g, f32x2 u) {
;     const f32x2 t = g * (-1.4426950409f);
;     f32x2 e; e.x = __builtin_amdgcn_exp2f(t.x); e.y = __builtin_amdgcn_exp2f(t.y);
;     const f32x2 d = e + 1.0f;
;     f32x2 r; r.x = __builtin_amdgcn_rcpf(d.x); r.y = __builtin_amdgcn_rcpf(d.y);
;     return (g * u) * r;
; }
;     __device__ __forceinline__ void operator()(const f32x4 (&acc)[2][2][4][2], const pg8::Unit& u, int wr, int wc, int fr_, int fq_) const {
;     ...
;             for (int m = 0; m < 4; ++m) {
;                 const int lr = lrow0 + ai * 128 + m * 16;
;                 const float rs = rs8[ai * 4 + m];
;                 const f32x4 g0 = acc[ai][0][m][0] * rs + sv[0][0], g1 = acc[ai][0][m][1] * rs + sv[0][1];
;                 const f32x4 u0 = acc[ai][1][m][0] * rs + sv[1][0], u1 = acc[ai][1][m][1] * rs + sv[1][1];
;                 const f32x2 ha = pg8::silu_mul_pk((f32x2){g0[0], g0[1]}, (f32x2){u0[0], u0[1]}), hb = pg8::silu_mul_pk((f32x2){g0[2], g0[3]}, (f32x2){u0[2], u0[3]});
;                 const f32x2 hc = pg8::silu_mul_pk((f32x2){g1[0], g1[1]}, (f32x2){u1[0], u1[1]}), hd = pg8::silu_mul_pk((f32x2){g1[2], g1[3]}, (f32x2){u1[2], u1[3]});
;                 u32x4 w; w.x = cvt_pk_bf16(ha.x, ha.y); w.y = cvt_pk_bf16(hb.x, hb.y); w.z = cvt_pk_bf16(hc.x, hc.y); w.w = cvt_pk_bf16(hd.x, hd.y);
;                 *(u32x4*)(H + (size_t)lr * FF + hcol) = w;
	v_exp_f32_e32 v97, v97
	v_mov_b32_e32 v160, v214
	v_pk_fma_f32 v[30:31], v[30:31], v[160:161], v[94:95] op_sel_hi:[1,0,1]
	v_pk_fma_f32 v[28:29], v[28:29], v[160:161], v[92:93] op_sel_hi:[1,0,1]
	v_pk_add_f32 v[96:97], v[96:97], 1.0 op_sel_hi:[1,0]
	v_pk_fma_f32 v[20:21], v[20:21], v[160:161], v[84:85] op_sel_hi:[1,0,1]
	v_rcp_f32_e32 v96, v96
	v_rcp_f32_e32 v97, v97
	v_pk_mul_f32 v[20:21], v[28:29], v[20:21]
	v_pk_fma_f32 v[22:23], v[22:23], v[160:161], v[86:87] op_sel_hi:[1,0,1]
	v_pk_fma_f32 v[24:25], v[24:25], v[160:161], v[88:89] op_sel_hi:[1,0,1]
	v_pk_mul_f32 v[106:107], v[98:99], v[96:97]
	v_cvt_pk_bf16_f32 v96, v100, v101
	v_mad_i64_i32 v[100:101], s[26:27], v114, s2, v[128:129]
	v_cvt_pk_bf16_f32 v97, v102, v103
	v_lshl_add_u64 v[100:101], v[100:101], 0, v[130:131]
	v_cvt_pk_bf16_f32 v98, v104, v105
	v_cvt_pk_bf16_f32 v99, v106, v107
	global_store_dwordx4 v[100:101], v[96:99], off
	v_pk_mul_f32 v[22:23], v[30:31], v[22:23]
	v_pk_fma_f32 v[16:17], v[16:17], v[160:161], v[80:81] op_sel_hi:[1,0,1]
	v_pk_mul_f32 v[96:97], v[76:77], s[88:89] op_sel_hi:[1,0]
	v_pk_mul_f32 v[76:77], v[78:79], s[88:89] op_sel_hi:[1,0]
	v_exp_f32_e32 v96, v96
	v_exp_f32_e32 v76, v76
	v_exp_f32_e32 v77, v77
	v_exp_f32_e32 v97, v97
	v_or_b32_e32 v98, 48, v165
	v_pk_fma_f32 v[26:27], v[26:27], v[160:161], v[90:91] op_sel_hi:[1,0,1]
	v_pk_add_f32 v[76:77], v[76:77], 1.0 op_sel_hi:[1,0]
	v_pk_add_f32 v[96:97], v[96:97], 1.0 op_sel_hi:[1,0]
	v_rcp_f32_e32 v76, v76
	v_rcp_f32_e32 v77, v77
	v_rcp_f32_e32 v96, v96
	v_rcp_f32_e32 v97, v97
	v_pk_mul_f32 v[16:17], v[24:25], v[16:17]
	v_pk_mul_f32 v[70:71], v[70:71], v[76:77]
	v_pk_mul_f32 v[76:77], v[72:73], s[88:89] op_sel_hi:[1,0]
	v_pk_mul_f32 v[68:69], v[68:69], v[96:97]
	v_exp_f32_e32 v76, v76
	v_exp_f32_e32 v77, v77
	v_pk_fma_f32 v[18:19], v[18:19], v[160:161], v[82:83] op_sel_hi:[1,0,1]
	v_pk_add_f32 v[76:77], v[76:77], 1.0 op_sel_hi:[1,0]
	v_rcp_f32_e32 v76, v76
	v_rcp_f32_e32 v77, v77
	v_pk_mul_f32 v[18:19], v[26:27], v[18:19]
	v_pk_mul_f32 v[72:73], v[64:65], v[76:77]
	v_pk_mul_f32 v[64:65], v[74:75], s[88:89] op_sel_hi:[1,0]
	v_exp_f32_e32 v64, v64
	v_exp_f32_e32 v65, v65
	v_mov_b32_e32 v158, v215
	v_pk_fma_f32 v[14:15], v[14:15], v[158:159], v[94:95] op_sel_hi:[1,0,1]
	v_pk_fma_f32 v[12:13], v[12:13], v[158:159], v[92:93] op_sel_hi:[1,0,1]
	v_pk_add_f32 v[64:65], v[64:65], 1.0 op_sel_hi:[1,0]
	v_pk_fma_f32 v[4:5], v[4:5], v[158:159], v[84:85] op_sel_hi:[1,0,1]
	v_rcp_f32_e32 v64, v64
	v_rcp_f32_e32 v65, v65
	v_pk_mul_f32 v[4:5], v[12:13], v[4:5]
	v_pk_fma_f32 v[6:7], v[6:7], v[158:159], v[86:87] op_sel_hi:[1,0,1]
	v_pk_fma_f32 v[8:9], v[8:9], v[158:159], v[88:89] op_sel_hi:[1,0,1]
	v_pk_mul_f32 v[74:75], v[66:67], v[64:65]
	v_cvt_pk_bf16_f32 v64, v68, v69
	v_mad_i64_i32 v[68:69], s[26:27], v98, s2, v[128:129]
	v_cvt_pk_bf16_f32 v65, v70, v71
	v_lshl_add_u64 v[68:69], v[68:69], 0, v[130:131]
	v_cvt_pk_bf16_f32 v66, v72, v73
	v_cvt_pk_bf16_f32 v67, v74, v75
	global_store_dwordx4 v[68:69], v[64:67], off
	v_pk_mul_f32 v[6:7], v[14:15], v[6:7]
	v_pk_fma_f32 v[0:1], v[0:1], v[158:159], v[80:81] op_sel_hi:[1,0,1]
	v_pk_mul_f32 v[64:65], v[60:61], s[88:89] op_sel_hi:[1,0]
	v_pk_mul_f32 v[60:61], v[62:63], s[88:89] op_sel_hi:[1,0]
	v_exp_f32_e32 v64, v64
	v_exp_f32_e32 v60, v60
	v_exp_f32_e32 v61, v61
	v_exp_f32_e32 v65, v65
	v_add_u32_e32 v66, 0x80, v165
	v_pk_fma_f32 v[10:11], v[10:11], v[158:159], v[90:91] op_sel_hi:[1,0,1]
	v_pk_add_f32 v[60:61], v[60:61], 1.0 op_sel_hi:[1,0]
	v_pk_add_f32 v[64:65], v[64:65], 1.0 op_sel_hi:[1,0]
	v_rcp_f32_e32 v60, v60
	v_rcp_f32_e32 v61, v61
	v_rcp_f32_e32 v64, v64
	v_rcp_f32_e32 v65, v65
	v_pk_mul_f32 v[0:1], v[8:9], v[0:1]
	v_pk_mul_f32 v[54:55], v[54:55], v[60:61]
	v_pk_mul_f32 v[60:61], v[56:57], s[88:89] op_sel_hi:[1,0]
	v_pk_mul_f32 v[52:53], v[52:53], v[64:65]
	v_exp_f32_e32 v60, v60
	v_exp_f32_e32 v61, v61
	v_pk_fma_f32 v[2:3], v[2:3], v[158:159], v[82:83] op_sel_hi:[1,0,1]
	s_andn2_b64 vcc, exec, s[36:37]
	v_pk_mul_f32 v[2:3], v[10:11], v[2:3]
	v_pk_add_f32 v[60:61], v[60:61], 1.0 op_sel_hi:[1,0]
	s_nop 0
	v_rcp_f32_e32 v60, v60
	v_rcp_f32_e32 v61, v61
	s_nop 0
	v_pk_mul_f32 v[56:57], v[48:49], v[60:61]
	v_pk_mul_f32 v[48:49], v[58:59], s[88:89] op_sel_hi:[1,0]
	s_nop 0
	v_exp_f32_e32 v48, v48
	v_exp_f32_e32 v49, v49
	s_nop 0
	v_pk_add_f32 v[48:49], v[48:49], 1.0 op_sel_hi:[1,0]
	s_nop 0
	v_rcp_f32_e32 v48, v48
	v_rcp_f32_e32 v49, v49
	s_nop 0
	v_pk_mul_f32 v[58:59], v[50:51], v[48:49]
	v_cvt_pk_bf16_f32 v48, v52, v53
; __device__ __forceinline__ unsigned cvt_pk_bf16(float lo, float hi) { unsigned r; asm volatile("v_cvt_pk_bf16_f32 %0, %1, %2" : "=v"(r) : "v"(lo), "v"(hi)); return r; }
; __device__ __forceinline__ f32x2 silu_mul_pk(f32x2 g, f32x2 u) {
;     const f32x2 t = g * (-1.4426950409f);
;     f32x2 e; e.x = __builtin_amdgcn_exp2f(t.x); e.y = __builtin_amdgcn_exp2f(t.y);
;     const f32x2 d = e + 1.0f;
;     f32x2 r; r.x = __builtin_amdgcn_rcpf(d.x); r.y = __builtin_amdgcn_rcpf(d.y);
;     return (g * u) * r;
; }
;     __device__ __forceinline__ void operator()(const f32x4 (&acc)[2][2][4][2], const pg8::Unit& u, int wr, int wc, int fr_, int fq_) const {
;     ...
;             for (int m = 0; m < 4; ++m) {
;                 const int lr = lrow0 + ai * 128 + m * 16;
;                 const float rs = rs8[ai * 4 + m];
;                 const f32x4 g0 = acc[ai][0][m][0] * rs + sv[0][0], g1 = acc[ai][0][m][1] * rs + sv[0][1];
;                 const f32x4 u0 = acc[ai][1][m][0] * rs + sv[1][0], u1 = acc[ai][1][m][1] * rs + sv[1][1];
;                 const f32x2 ha = pg8::silu_mul_pk((f32x2){g0[0], g0[1]}, (f32x2){u0[0], u0[1]}), hb = pg8::silu_mul_pk((f32x2){g0[2], g0[3]}, (f32x2){u0[2], u0[3]});
;                 const f32x2 hc = pg8::silu_mul_pk((f32x2){g1[0], g1[1]}, (f32x2){u1[0], u1[1]}), hd = pg8::silu_mul_pk((f32x2){g1[2], g1[3]}, (f32x2){u1[2], u1[3]});
;                 u32x4 w; w.x = cvt_pk_bf16(ha.x, ha.y); w.y = cvt_pk_bf16(hb.x, hb.y); w.z = cvt_pk_bf16(hc.x, hc.y); w.w = cvt_pk_bf16(hd.x, hd.y);
;                 *(u32x4*)(H + (size_t)lr * FF + hcol) = w;
;             }
	v_mad_i64_i32 v[52:53], s[26:27], v66, s2, v[128:129]
	v_cvt_pk_bf16_f32 v49, v54, v55
	v_lshl_add_u64 v[52:53], v[52:53], 0, v[130:131]
	v_cvt_pk_bf16_f32 v50, v56, v57
	v_cvt_pk_bf16_f32 v51, v58, v59
	global_store_dwordx4 v[52:53], v[48:51], off
	s_nop 1
	v_pk_mul_f32 v[48:49], v[44:45], s[88:89] op_sel_hi:[1,0]
	v_pk_mul_f32 v[44:45], v[46:47], s[88:89] op_sel_hi:[1,0]
	v_exp_f32_e32 v48, v48
	v_exp_f32_e32 v44, v44
	v_exp_f32_e32 v45, v45
	v_exp_f32_e32 v49, v49
	v_add_u32_e32 v50, 0x90, v165
	v_pk_add_f32 v[44:45], v[44:45], 1.0 op_sel_hi:[1,0]
	s_nop 0
	v_rcp_f32_e32 v44, v44
	v_rcp_f32_e32 v45, v45
	v_pk_add_f32 v[48:49], v[48:49], 1.0 op_sel_hi:[1,0]
	v_pk_mul_f32 v[38:39], v[38:39], v[44:45]
	v_pk_mul_f32 v[44:45], v[40:41], s[88:89] op_sel_hi:[1,0]
	v_rcp_f32_e32 v48, v48
	v_exp_f32_e32 v44, v44
	v_exp_f32_e32 v45, v45
	v_rcp_f32_e32 v49, v49
	v_pk_add_f32 v[44:45], v[44:45], 1.0 op_sel_hi:[1,0]
	s_nop 0
	v_rcp_f32_e32 v44, v44
	v_rcp_f32_e32 v45, v45
	v_pk_mul_f32 v[36:37], v[36:37], v[48:49]
	v_pk_mul_f32 v[40:41], v[32:33], v[44:45]
	v_pk_mul_f32 v[32:33], v[42:43], s[88:89] op_sel_hi:[1,0]
	s_nop 0
	v_exp_f32_e32 v32, v32
	v_exp_f32_e32 v33, v33
	s_nop 0
	v_pk_add_f32 v[32:33], v[32:33], 1.0 op_sel_hi:[1,0]
	s_nop 0
	v_rcp_f32_e32 v32, v32
	v_rcp_f32_e32 v33, v33
	s_nop 0
	v_pk_mul_f32 v[42:43], v[34:35], v[32:33]
	v_cvt_pk_bf16_f32 v32, v36, v37
	v_mad_i64_i32 v[36:37], s[26:27], v50, s2, v[128:129]
	v_cvt_pk_bf16_f32 v33, v38, v39
	v_lshl_add_u64 v[36:37], v[36:37], 0, v[130:131]
	v_cvt_pk_bf16_f32 v34, v40, v41
	v_cvt_pk_bf16_f32 v35, v42, v43
	global_store_dwordx4 v[36:37], v[32:35], off
	s_nop 1
	v_pk_mul_f32 v[32:33], v[28:29], s[88:89] op_sel_hi:[1,0]
	v_pk_mul_f32 v[28:29], v[30:31], s[88:89] op_sel_hi:[1,0]
	v_exp_f32_e32 v32, v32
	v_exp_f32_e32 v28, v28
	v_exp_f32_e32 v29, v29
	v_exp_f32_e32 v33, v33
	v_add_u32_e32 v34, 0xa0, v165
	v_pk_add_f32 v[28:29], v[28:29], 1.0 op_sel_hi:[1,0]
	s_nop 0
	v_rcp_f32_e32 v28, v28
	v_rcp_f32_e32 v29, v29
	v_pk_add_f32 v[32:33], v[32:33], 1.0 op_sel_hi:[1,0]
	v_pk_mul_f32 v[22:23], v[22:23], v[28:29]
	v_pk_mul_f32 v[28:29], v[24:25], s[88:89] op_sel_hi:[1,0]
	v_rcp_f32_e32 v32, v32
	v_exp_f32_e32 v28, v28
	v_exp_f32_e32 v29, v29
	v_rcp_f32_e32 v33, v33
	v_pk_add_f32 v[28:29], v[28:29], 1.0 op_sel_hi:[1,0]
	s_nop 0
	v_rcp_f32_e32 v28, v28
	v_rcp_f32_e32 v29, v29
	v_pk_mul_f32 v[20:21], v[20:21], v[32:33]
	v_pk_mul_f32 v[24:25], v[16:17], v[28:29]
	v_pk_mul_f32 v[16:17], v[26:27], s[88:89] op_sel_hi:[1,0]
	s_nop 0
	v_exp_f32_e32 v16, v16
	v_exp_f32_e32 v17, v17
	s_nop 0
	v_pk_add_f32 v[16:17], v[16:17], 1.0 op_sel_hi:[1,0]
	s_nop 0
	v_rcp_f32_e32 v16, v16
	v_rcp_f32_e32 v17, v17
	s_nop 0
	v_pk_mul_f32 v[26:27], v[18:19], v[16:17]
	v_cvt_pk_bf16_f32 v16, v20, v21
	v_mad_i64_i32 v[20:21], s[26:27], v34, s2, v[128:129]
	v_cvt_pk_bf16_f32 v17, v22, v23
	v_lshl_add_u64 v[20:21], v[20:21], 0, v[130:131]
	v_cvt_pk_bf16_f32 v18, v24, v25
	v_cvt_pk_bf16_f32 v19, v26, v27
	global_store_dwordx4 v[20:21], v[16:19], off
	s_nop 1
	v_pk_mul_f32 v[16:17], v[12:13], s[88:89] op_sel_hi:[1,0]
	v_pk_mul_f32 v[12:13], v[14:15], s[88:89] op_sel_hi:[1,0]
	v_exp_f32_e32 v16, v16
	v_exp_f32_e32 v12, v12
	v_exp_f32_e32 v13, v13
	v_exp_f32_e32 v17, v17
	v_add_u32_e32 v18, 0xb0, v165
	v_pk_add_f32 v[12:13], v[12:13], 1.0 op_sel_hi:[1,0]
	s_nop 0
	v_rcp_f32_e32 v12, v12
	v_rcp_f32_e32 v13, v13
	v_pk_add_f32 v[16:17], v[16:17], 1.0 op_sel_hi:[1,0]
	v_pk_mul_f32 v[6:7], v[6:7], v[12:13]
	v_pk_mul_f32 v[12:13], v[8:9], s[88:89] op_sel_hi:[1,0]
	v_rcp_f32_e32 v16, v16
	v_exp_f32_e32 v12, v12
	v_exp_f32_e32 v13, v13
	v_rcp_f32_e32 v17, v17
	v_pk_add_f32 v[12:13], v[12:13], 1.0 op_sel_hi:[1,0]
	s_nop 0
	v_rcp_f32_e32 v12, v12
	v_rcp_f32_e32 v13, v13
	v_pk_mul_f32 v[4:5], v[4:5], v[16:17]
	v_pk_mul_f32 v[8:9], v[0:1], v[12:13]
	v_pk_mul_f32 v[0:1], v[10:11], s[88:89] op_sel_hi:[1,0]
	s_nop 0
	v_exp_f32_e32 v0, v0
	v_exp_f32_e32 v1, v1
	s_nop 0
	v_pk_add_f32 v[0:1], v[0:1], 1.0 op_sel_hi:[1,0]
	s_nop 0
	v_rcp_f32_e32 v0, v0
	v_rcp_f32_e32 v1, v1
	s_nop 0
	v_pk_mul_f32 v[10:11], v[2:3], v[0:1]
	v_cvt_pk_bf16_f32 v0, v4, v5
	v_mad_i64_i32 v[4:5], s[26:27], v18, s2, v[128:129]
	v_lshl_add_u64 v[4:5], v[4:5], 0, v[130:131]
	s_mov_b64 s[26:27], -1
	v_cvt_pk_bf16_f32 v1, v6, v7
	v_cvt_pk_bf16_f32 v2, v8, v9
	v_cvt_pk_bf16_f32 v3, v10, v11
	global_store_dwordx4 v[4:5], v[0:3], off
	s_cbranch_vccnz .LBB0_369
	s_and_b64 vcc, exec, s[34:35]
	s_cbranch_vccnz .LBB0_368
	s_barrier
	s_branch .LBB0_368
